# CEN1: first-barrier census reads its 16 per-XCC counters with 16 loads in flight and one wait (was 16 serial round trips), on top of v061
# baseline (speedup 1.0000x reference)
.LBB0_409:
	v_readlane_b32 s28, v249, 34
	v_readlane_b32 s29, v249, 35
	s_mov_b64 s[34:35], -1
	s_waitcnt lgkmcnt(0)
	s_nop 3
	global_load_dword v1, v0, s[28:29] sc1
	global_load_dword v2, v0, s[28:29] offset:256 sc1
	global_load_dword v3, v0, s[28:29] offset:512 sc1
	global_load_dword v4, v0, s[28:29] offset:768 sc1
	global_load_dword v5, v0, s[28:29] offset:1024 sc1
	global_load_dword v6, v0, s[28:29] offset:1280 sc1
	global_load_dword v7, v0, s[28:29] offset:1536 sc1
	global_load_dword v8, v0, s[28:29] offset:1792 sc1
	global_load_dword v9, v0, s[28:29] offset:2048 sc1
	global_load_dword v10, v0, s[28:29] offset:2304 sc1
	global_load_dword v11, v0, s[28:29] offset:2560 sc1
	global_load_dword v12, v0, s[28:29] offset:2816 sc1
	global_load_dword v13, v0, s[28:29] offset:3072 sc1
	global_load_dword v14, v0, s[28:29] offset:3328 sc1
	global_load_dword v15, v0, s[28:29] offset:3584 sc1
	global_load_dword v16, v0, s[28:29] offset:3840 sc1
	s_mov_b64 s[28:29], -1
	s_waitcnt vmcnt(0)
	v_add_u32_e32 v17, v2, v1
	v_add_u32_e32 v17, v17, v3
	v_add_u32_e32 v17, v17, v4
	v_add_u32_e32 v17, v17, v5
	v_add_u32_e32 v17, v17, v6
	v_add_u32_e32 v17, v17, v7
	v_add_u32_e32 v17, v17, v8
	v_add_u32_e32 v17, v17, v9
	v_add_u32_e32 v17, v17, v10
	v_add_u32_e32 v17, v17, v11
	v_add_u32_e32 v17, v17, v12
	v_add_u32_e32 v17, v17, v13
	v_add_u32_e32 v17, v17, v14
	v_add_u32_e32 v17, v17, v15
	v_add_u32_e32 v17, v17, v16
	v_cmp_eq_u32_e32 vcc, s90, v17
	s_cbranch_vccnz .LBB0_408
	s_and_b32 s1, s0, 0xff
	s_cmp_eq_u32 s1, 0
	s_mov_b64 s[38:39], -1
	s_sleep 1
	s_cbranch_scc1 .LBB0_413
	s_and_b64 vcc, exec, s[38:39]
	s_cbranch_vccz .LBB0_408
